# window-branch tile 0 of an NSA unit is fetched at the start of the selected-block loop (parked in free registers) instead of after it
# speedup vs baseline: 1.0093x; 1.0017x over previous
; DI int tid_now() { int t = threadIdx.x; asm volatile("" : "+v"(t)); return t; }
;     DI float* h() const { return (float*)(__attribute__((address_space(1))) float*)kp->out; }
; template <bool MLA> DI void tile_gload(TileRegs& R, const bf16_t* kp, size_t kst, const bf16_t* vp, size_t vst, const bf16_t* k2p, int kb, int tid) {
;     const int key = tid >> 3, c = tid & 7;
;     R.k = *(const u32x4*)(kp + (size_t)(kb + key) * kst + 8 * c);
;     R.v = *(const u32x4*)(vp + (size_t)(kb + (tid & 63)) * vst + 8 * (tid >> 6));
;     if (MLA) R.k2 = *(const u32x4*)(k2p + (size_t)(kb + ((tid & 255) >> 2)) * 32 + 8 * (tid & 3));
; }
; DI void unit_nsa(Frame& F, int b, int g, int qt, int tid) {
;     ...
;     { const int r = tid_now() & 31, h = (tid_now() >> 5) & 1; CfNsa<false> cw{Q, O, m, l, t, r, h, sl2, 0ull}; att_pipe<false>(KB, VB, zb + Z_KW + g * 64, ZP, zb + Z_VW + g * 64, ZP, nullptr, TlRangeDesc{qt >= 8 ? qt - 8 : 0, qt}, cw, tid); }
.LBB0_1428:
	v_readfirstlane_b32 s52, v138
	s_lshl_b32 s24, s42, 1
	s_add_u32 s24, s22, s24
	s_addc_u32 s25, s23, 0
	v_ashrrev_i32_e32 v250, 3, v214
	v_add_u32_e32 v236, s96, v250
	v_ashrrev_i32_e32 v237, 31, v236
	v_lshlrev_b64 v[236:237], 12, v[236:237]
	v_lshlrev_b32_e32 v238, 4, v214
	v_and_b32_e32 v238, 0x70, v238
	v_mov_b32_e32 v239, 0
	v_lshl_add_u64 v[236:237], s[24:25], 0, v[236:237]
	v_lshl_add_u64 v[236:237], v[236:237], 0, v[238:239]
	v_and_b32_e32 v248, 63, v214
	v_or_b32_e32 v248, s96, v248
	v_lshlrev_b32_e32 v248, 12, v248
	v_mov_b32_e32 v249, 0
	v_and_b32_e32 v250, -8, v250
	v_lshlrev_b32_e32 v250, 1, v250
	v_mov_b32_e32 v251, 0
	v_lshl_add_u64 v[248:249], s[24:25], 0, v[248:249]
	v_lshl_add_u64 v[248:249], v[248:249], 0, v[250:251]
	global_load_dwordx4 v[240:243], v[236:237], off offset:3072
	global_load_dwordx4 v[244:247], v[248:249], off offset:3840

; template <bool MLA, class TL, class CF>
; DI void att_pipe(lbf KB, lbf VB, const bf16_t* kp, size_t kst, const bf16_t* vp, size_t vst, const bf16_t* k2p, const TL& tl, CF& cf, int) {
;     ...
;     TileRegs R0, R1; tile_gload<MLA>(R0, kp, kst, vp, vst, k2p, kb, tid);
;     int nk = tl.next(kb);
;     tile_gload<MLA>(R1, kp, kst, vp, vst, k2p, nk >= 0 ? nk : kb, tid);
;     __syncthreads();
;     tile_lstore<MLA>(R0, KB, VB, tid);
;     __syncthreads();
.LBB0_1454:
	v_mov_b32_e32 v187, v186
	v_mov_b32_e32 v82, v214
	v_mov_b32_e32 v83, v214
	v_mov_b32_e32 v84, v214
	s_lshl_b32 s16, s42, 1
	v_ashrrev_i32_e32 v210, 3, v84
	s_waitcnt vmcnt(0)
	v_add_u32_e32 v2, s96, v210
	v_and_b32_e32 v211, 63, v84
	s_add_u32 s16, s22, s16
	v_ashrrev_i32_e32 v3, 31, v2
	v_or_b32_e32 v4, s96, v211
	v_and_b32_e32 v12, -8, v210
	s_addc_u32 s17, s23, 0
	v_lshlrev_b64 v[2:3], 12, v[2:3]
	v_lshlrev_b32_e32 v0, 4, v84
	v_lshlrev_b32_e32 v4, 12, v4
	v_mov_b32_e32 v5, v1
	v_ashrrev_i32_e32 v13, 31, v12
	v_lshl_add_u64 v[2:3], s[16:17], 0, v[2:3]
	v_and_b32_e32 v0, 0x70, v0
	v_lshl_add_u64 v[4:5], s[16:17], 0, v[4:5]
	v_lshlrev_b64 v[14:15], 1, v[12:13]
	v_lshl_add_u64 v[2:3], v[2:3], 0, v[0:1]
	v_lshl_add_u64 v[8:9], v[4:5], 0, v[14:15]
	s_nop 0
	s_nop 0
	s_nop 0
	v_sub_u32_e64 v2, 55, s97 clamp
	s_sub_i32 s23, s96, 64
	v_readfirstlane_b32 s22, v2
	s_lshl_b32 s22, s22, 6
	s_cmp_gt_u32 s96, s22
	s_cselect_b32 s23, s23, -1
	s_cmp_lt_i32 s23, 0
	s_cselect_b32 s24, s96, s23
	v_add_u32_e32 v2, s24, v210
	v_ashrrev_i32_e32 v3, 31, v2
	v_add_u32_e32 v80, s24, v211
	v_lshlrev_b64 v[2:3], 12, v[2:3]
	v_ashrrev_i32_e32 v81, 31, v80
	v_lshl_add_u64 v[2:3], s[16:17], 0, v[2:3]
	v_lshlrev_b64 v[80:81], 12, v[80:81]
	v_lshl_add_u64 v[2:3], v[2:3], 0, v[0:1]
	v_lshl_add_u64 v[80:81], s[16:17], 0, v[80:81]
	v_lshl_add_u64 v[80:81], v[80:81], 0, v[14:15]
	global_load_dwordx4 v[164:167], v[2:3], off offset:3072
	global_load_dwordx4 v[160:163], v[80:81], off offset:3840
	v_and_b32_e32 v13, 31, v82
	v_and_b32_e32 v81, 51, v84
	v_lshlrev_b32_e32 v82, 2, v84
	v_bfe_u32 v80, v83, 5, 1
	v_and_b32_e32 v83, 8, v84
	s_movk_i32 s24, 0x90
	v_lshl_add_u32 v81, v81, 1, 0
	v_and_b32_e32 v82, 16, v82
	v_or_b32_e32 v85, 7, v210
	v_mul_lo_u32 v84, v210, s24
	v_mul_u32_u24_e32 v86, 0x90, v13
	v_sub_u32_e32 v213, v205, v13
	v_lshlrev_b32_e32 v13, 4, v80
	v_add3_u32 v235, v81, v82, v83
	v_mul_lo_u32 v236, v12, s24
	v_mul_lo_u32 v237, v85, s24
	v_add3_u32 v234, 0, v84, v0
	v_add3_u32 v238, 0, v86, v13
	v_add_u32_e32 v12, v235, v236
	v_add_u32_e32 v13, v235, v237
	v_lshl_add_u64 v[190:191], s[16:17], 0, v[14:15]
	v_mov_b32_e32 v14, v1
	v_mov_b32_e32 v15, v1
	v_mov_b32_e32 v2, v1
	v_mov_b32_e32 v3, v1
	v_lshlrev_b32_e32 v233, 2, v80
	v_lshl_add_u64 v[188:189], s[16:17], 0, v[0:1]
	v_mov_b32_e32 v0, v1
	s_waitcnt lgkmcnt(0)
	s_barrier
	s_mov_b32 s42, 0
	v_mov_b32_e32 v212, 0
	v_mov_b32_e32 v239, 0xf149f2ca
	s_waitcnt vmcnt(3)
	ds_write_b128 v234, v[240:243]
	s_waitcnt vmcnt(2)
	ds_write_b16 v12, v244 offset:26624
	ds_write_b16_d16_hi v12, v244 offset:26768
	ds_write_b16 v12, v245 offset:26912
	ds_write_b16_d16_hi v12, v245 offset:27056
	ds_write_b16 v12, v246 offset:27200
	ds_write_b16_d16_hi v12, v246 offset:27344
	ds_write_b16 v12, v247 offset:27488
	ds_write_b16_d16_hi v13, v247 offset:26624
	v_mov_b32_e32 v4, v1
	v_mov_b32_e32 v5, v1
	v_mov_b32_e32 v6, v1
	v_mov_b32_e32 v7, v1
	v_mov_b32_e32 v8, v1
	v_mov_b32_e32 v9, v1
	v_mov_b32_e32 v10, v1
	v_mov_b32_e32 v11, v1
	v_mov_b32_e32 v12, v1
	v_mov_b32_e32 v13, v1
	v_mov_b64_e32 v[110:111], v[14:15]
	v_mov_b64_e32 v[94:95], v[14:15]
	v_mov_b64_e32 v[108:109], v[12:13]
	v_mov_b64_e32 v[106:107], v[10:11]
	v_mov_b64_e32 v[104:105], v[8:9]
	v_mov_b64_e32 v[102:103], v[6:7]
	v_mov_b64_e32 v[100:101], v[4:5]
	v_mov_b64_e32 v[98:99], v[2:3]
	v_mov_b64_e32 v[96:97], v[0:1]
	v_mov_b64_e32 v[92:93], v[12:13]
	v_mov_b64_e32 v[90:91], v[10:11]
	v_mov_b64_e32 v[88:89], v[8:9]
	v_mov_b64_e32 v[86:87], v[6:7]
	v_mov_b64_e32 v[84:85], v[4:5]
	v_mov_b64_e32 v[82:83], v[2:3]
	v_mov_b64_e32 v[80:81], v[0:1]
	s_waitcnt lgkmcnt(0)
	s_barrier
	s_branch .LBB0_1456

; DI int tid_now() { int t = threadIdx.x; asm volatile("" : "+v"(t)); return t; }
;     DI float* h() const { return (float*)(__attribute__((address_space(1))) float*)kp->out; }
; DI void unit_nsa(Frame& F, int b, int g, int qt, int tid) {
;     ...
;     { const int r = tid_now() & 31, h = (tid_now() >> 5) & 1; CfNsa<true> cs{Q, O, m, l, t, r, h, sl2, qsel}; att_pipe<false>(KB, VB, zb + Z_KS + g * 64, ZP, zb + Z_VS + g * 64, ZP, nullptr, TlMaskDesc{umask}, cs, tid); }
;     ...
;     { const int r = tid_now() & 31, h = (tid_now() >> 5) & 1; CfNsa<false> cw{Q, O, m, l, t, r, h, sl2, 0ull}; att_pipe<false>(KB, VB, zb + Z_KW + g * 64, ZP, zb + Z_VW + g * 64, ZP, nullptr, TlRangeDesc{qt >= 8 ? qt - 8 : 0, qt}, cw, tid); }
.LBB0_1509:
	s_lshl_b32 s24, s42, 1
	s_add_u32 s24, s22, s24
	s_addc_u32 s25, s23, 0
	v_ashrrev_i32_e32 v250, 3, v214
	v_add_u32_e32 v236, s96, v250
	v_ashrrev_i32_e32 v237, 31, v236
	v_lshlrev_b64 v[236:237], 12, v[236:237]
	v_lshlrev_b32_e32 v238, 4, v214
	v_and_b32_e32 v238, 0x70, v238
	v_mov_b32_e32 v239, 0
	v_lshl_add_u64 v[236:237], s[24:25], 0, v[236:237]
	v_lshl_add_u64 v[236:237], v[236:237], 0, v[238:239]
	v_and_b32_e32 v248, 63, v214
	v_or_b32_e32 v248, s96, v248
	v_lshlrev_b32_e32 v248, 12, v248
	v_mov_b32_e32 v249, 0
	v_and_b32_e32 v250, -8, v250
	v_lshlrev_b32_e32 v250, 1, v250
	v_mov_b32_e32 v251, 0
	v_lshl_add_u64 v[248:249], s[24:25], 0, v[248:249]
	v_lshl_add_u64 v[248:249], v[248:249], 0, v[250:251]
	global_load_dwordx4 v[240:243], v[236:237], off offset:3072
	global_load_dwordx4 v[244:247], v[248:249], off offset:3840
	s_cbranch_execnz .LBB0_1453
	s_branch .LBB0_1454
